# previous plus generic GEMM prologue: second k-tile LDS-DMA loads issued before the first wait and barrier (one memory round trip less per GEMM phase)
# baseline (speedup 1.0000x reference)
; #define PG8_STAGE(bufoff, gbase, voff) do { _Pragma("unroll") for (int _i = 0; _i < 2; ++_i) \
;         __builtin_amdgcn_global_load_lds((const unsigned*)((const char*)(gbase) + (voff)[_i]), (PG8_LAS unsigned*)(lds + (bufoff) + ldsw + _i * 8192), 16, 0, 0); } while (0)
; #define PG8_WAIT_V(n) asm volatile("s_waitcnt vmcnt(" #n ")" ::: "memory")
; #define PG8_BAR __builtin_amdgcn_s_barrier()
; template <class Epi, class Sched, bool ALIGN_EPI = false>
; __device__ __forceinline__ void gemm_phase(PG8_LAS unsigned char* lds, const Gemm g, const Sched& S, const Epi& E, int tid_in) {
;     ...
;     for (int i = 0; i < 2; ++i) { int R, C; stage_rc(tid * 16 + i * 8192, R, C); const int Rb = E.perm() ? ((R & ~31) + perm32(R & 31)) : R;
;         voffA[i] = (unsigned)(R * lda + C) * 2u; voffB[i] = (unsigned)(Rb * ldb + C) * 2u; }
;     const size_t kstep = (size_t)(BK * 2);
;     const size_t hstepA = (size_t)HALF * lda * 2, hstepB = (size_t)HALF * ldb * 2;
;     const size_t tstepA = 2 * hstepA, tstepB = 2 * hstepB;
;     const unsigned ldsw = (unsigned)wid * 1024u;
;     const int aoff = lds_byte(wr * 64 + fr, fq * 8), boff = lds_byte(wc * 32 + fr, fq * 8);
;     ...
;     Unit cur, nxt; int ui = 0;
;     if (!S.next(0, cur)) return;
;     f32x4 acc[2][2][4][2];
;     E.init(acc, cur, wr, wc, fr, fq);
;     bf16x8 At[4][2], B0[2][2], B1[2][2];
;     const char* cA = (const char*)g.A + (size_t)cur.pm * tstepA; const char* cB = (const char*)g.Bt + (size_t)cur.pn * tstepB;
;     S.a_ready(cur);
;     PG8_STAGE(PG8_SB(0, 0), cB, voffB); PG8_STAGE(PG8_SB(0, 1), cB + hstepB, voffB); PG8_STAGE(PG8_SA(0, 0), cA, voffA); PG8_STAGE(PG8_SA(0, 1), cA + hstepA, voffA);
;     if (wr == 1) PG8_BAR;
;     PG8_WAIT_V(2); PG8_BAR;
;     PG8_STAGE(PG8_SB(1, 0), cB + kstep, voffB); PG8_STAGE(PG8_SA(1, 0), cA + kstep, voffA); PG8_STAGE(PG8_SB(1, 1), cB + hstepB + kstep, voffB);
;     PG8_WAIT_V(6); PG8_BAR;
.LBB0_252:
	v_ashrrev_i32_e32 v131, 31, v80
	v_lshrrev_b32_e32 v131, 26, v131
	v_lshlrev_b32_e32 v130, 4, v80
	v_add_u32_e32 v131, v80, v131
	v_bfe_i32 v80, v80, 27, 1
	v_lshrrev_b32_e32 v80, 22, v80
	v_add_u32_e32 v80, v130, v80
	v_and_b32_e32 v80, 0xfffffc00, v80
	v_sub_u32_e32 v80, v130, v80
	v_lshrrev_b32_e32 v132, 4, v80
	v_bitop3_b32 v80, v132, v80, 32 bitop3:0x6c
	v_ashrrev_i32_e32 v133, 31, v80
	v_ashrrev_i32_e32 v131, 6, v131
	v_lshrrev_b32_e32 v133, 26, v133
	v_lshlrev_b32_e32 v132, 3, v131
	v_add_u32_e32 v133, v80, v133
	v_and_b32_e32 v132, -16, v132
	v_ashrrev_i32_e32 v134, 6, v133
	v_lshlrev_b32_e32 v131, 5, v131
	v_add_u32_e32 v132, v134, v132
	v_and_b32_e32 v144, 32, v131
	v_and_b32_e32 v131, 0xc0, v133
	v_sub_u32_e32 v80, v80, v131
	v_lshlrev_b32_e32 v131, 1, v132
	v_lshrrev_b32_e32 v133, 2, v132
	v_and_b32_e32 v134, 3, v134
	s_mov_b32 s0, 0x7fffffe0
	v_ashrrev_i16_sdwa v80, v221, sext(v80) dst_sel:DWORD dst_unused:UNUSED_PAD src0_sel:DWORD src1_sel:BYTE_0
	v_and_b32_e32 v131, 24, v131
	v_and_b32_e32 v133, 4, v133
	v_and_or_b32 v134, v132, s0, v134
	v_bfe_i32 v145, v80, 0, 16
	v_or3_b32 v131, v134, v133, v131
	v_add_u32_e32 v80, v144, v145
	v_mul_lo_u32 v146, v132, s20
	v_mul_lo_u32 v131, v131, s16
	v_add_lshl_u32 v184, v80, v146, 1
	v_add_lshl_u32 v186, v131, v80, 1
	v_add_u32_e32 v80, 0x2000, v130
	v_ashrrev_i32_e32 v130, 31, v80
	v_lshrrev_b32_e32 v130, 22, v130
	v_add_u32_e32 v130, v80, v130
	v_ashrrev_i32_e32 v130, 10, v130
	v_mul_i32_i24_e32 v131, 0x400, v130
	v_sub_u32_e32 v80, v80, v131
	v_lshrrev_b32_e32 v131, 4, v80
	v_bitop3_b32 v80, v131, v80, 32 bitop3:0x6c
	v_writelane_b32 v254, s79, 6
	v_ashrrev_i32_e32 v132, 31, v80
	v_writelane_b32 v254, s68, 7
	v_lshrrev_b32_e32 v132, 26, v132
	v_lshlrev_b32_e32 v131, 3, v130
	v_writelane_b32 v254, s69, 8
	v_add_u32_e32 v132, v80, v132
	v_writelane_b32 v254, s70, 9
	v_and_b32_e32 v131, -16, v131
	v_ashrrev_i32_e32 v133, 6, v132
	v_writelane_b32 v254, s71, 10
	v_add_u32_e32 v131, v133, v131
	v_lshlrev_b32_e32 v130, 5, v130
	v_and_b32_e32 v133, 3, v133
	s_lshl_b32 s68, s16, 9
	v_and_b32_e32 v147, 32, v130
	v_and_b32_e32 v130, 0xc0, v132
	v_and_or_b32 v133, v131, s0, v133
	s_lshl_b32 s0, s20, 8
	s_lshl_b32 s33, s16, 8
	s_lshl_b32 s67, s20, 9
	s_lshl_b32 s69, s12, 10
	s_mul_i32 s13, s68, s87
	v_sub_u32_e32 v80, v80, v130
	v_lshlrev_b32_e32 v130, 1, v131
	v_lshrrev_b32_e32 v132, 2, v131
	s_mul_hi_i32 s12, s68, s87
	s_add_u32 s58, s4, s13
	v_ashrrev_i16_sdwa v80, v221, sext(v80) dst_sel:DWORD dst_unused:UNUSED_PAD src0_sel:DWORD src1_sel:BYTE_0
	v_and_b32_e32 v130, 24, v130
	v_and_b32_e32 v132, 4, v132
	s_addc_u32 s59, s5, s12
	s_add_i32 s70, s69, 0
	v_bfe_i32 v148, v80, 0, 16
	v_or3_b32 v130, v133, v132, v130
	s_add_i32 m0, s70, 0x10000
	v_add_u32_e32 v80, v147, v148
	v_mul_lo_u32 v130, v130, s16
	global_load_lds_dwordx4 v186, s[58:59]
	s_add_i32 m0, s70, 0x12000
	v_add_lshl_u32 v190, v130, v80, 1
	s_add_u32 s12, s58, s33
	global_load_lds_dwordx4 v190, s[58:59]
	s_addc_u32 s13, s59, 0
	s_add_i32 m0, s70, 0x14000
	s_mul_i32 s15, s67, s88
	global_load_lds_dwordx4 v186, s[12:13]
	s_add_i32 m0, s70, 0x16000
	s_mul_hi_i32 s14, s67, s88
	s_add_u32 s60, s8, s15
	v_mov_b32_e32 v187, v81
	v_mov_b32_e32 v191, v81
	s_addc_u32 s61, s9, s14
	s_add_i32 s71, s70, 0x2000
	v_mul_lo_u32 v149, v131, s20
	v_lshl_add_u64 v[134:135], s[12:13], 0, v[186:187]
	v_lshl_add_u64 v[136:137], s[12:13], 0, v[190:191]
	global_load_lds_dwordx4 v190, s[12:13]
	s_mov_b32 m0, s70
	s_add_u32 s12, s60, s0
	v_add_lshl_u32 v188, v80, v149, 1
	global_load_lds_dwordx4 v184, s[60:61]
	s_mov_b32 m0, s71
	s_addc_u32 s13, s61, 0
	s_add_i32 s72, s70, 0x4000
	global_load_lds_dwordx4 v188, s[60:61]
	s_mov_b32 m0, s72
	s_add_i32 s73, s70, 0x6000
	global_load_lds_dwordx4 v184, s[12:13]
	s_mov_b32 m0, s73
	v_writelane_b32 v255, s84, 36
	global_load_lds_dwordx4 v188, s[12:13]
	v_mov_b32_e32 v185, v81
	v_mov_b32_e32 v189, v81
	s_cmp_eq_u32 s21, 1
	v_writelane_b32 v255, s85, 37
	s_mov_b64 s[94:95], s[82:83]
	s_mov_b32 s1, s24
	v_lshl_add_u64 v[130:131], s[58:59], 0, v[186:187]
	v_lshl_add_u64 v[132:133], s[58:59], 0, v[190:191]
	v_lshl_add_u64 v[138:139], s[60:61], 0, v[184:185]
	v_lshl_add_u64 v[140:141], s[60:61], 0, v[188:189]
	s_add_i32 m0, s70, 0x18000
	v_lshl_add_u64 v[130:131], v[130:131], 0, s[96:97]
	s_add_i32 s74, s70, 0x8000
	global_load_lds_dwordx4 v[130:131], off
	v_lshl_add_u64 v[130:131], v[132:133], 0, s[96:97]
	s_add_i32 m0, s70, 0x1a000
	s_add_i32 s75, s70, 0xa000
	global_load_lds_dwordx4 v[130:131], off
	v_or_b32_e32 v244, s66, v243
	s_add_i32 m0, s70, 0x1c000
	v_lshl_add_u64 v[130:131], v[134:135], 0, s[96:97]
	global_load_lds_dwordx4 v[130:131], off
	v_lshl_add_u64 v[130:131], v[136:137], 0, s[96:97]
	s_add_i32 m0, s70, 0x1e000
	v_lshlrev_b32_e32 v80, 4, v143
	global_load_lds_dwordx4 v[130:131], off
	s_cmp_eq_u32 s21, 1
	s_cselect_b64 s[12:13], -1, 0
	s_cmp_lg_u32 s21, 1
	s_cbranch_scc1 .LBB0_254
	s_barrier
; #define PG8_STAGE(bufoff, gbase, voff) do { _Pragma("unroll") for (int _i = 0; _i < 2; ++_i) \
;         __builtin_amdgcn_global_load_lds((const unsigned*)((const char*)(gbase) + (voff)[_i]), (PG8_LAS unsigned*)(lds + (bufoff) + ldsw + _i * 8192), 16, 0, 0); } while (0)
; #define PG8_WAIT_V(n) asm volatile("s_waitcnt vmcnt(" #n ")" ::: "memory")
; #define PG8_BAR __builtin_amdgcn_s_barrier()
; template <class Epi, class Sched, bool ALIGN_EPI = false>
; __device__ __forceinline__ void gemm_phase(PG8_LAS unsigned char* lds, const Gemm g, const Sched& S, const Epi& E, int tid_in) {
;     ...
;     const unsigned ldsw = (unsigned)wid * 1024u;
;     const int aoff = lds_byte(wr * 64 + fr, fq * 8), boff = lds_byte(wc * 32 + fr, fq * 8);
;     ...
;     if (wr == 1) PG8_BAR;
;     PG8_WAIT_V(2); PG8_BAR;
;     PG8_STAGE(PG8_SB(1, 0), cB + kstep, voffB); PG8_STAGE(PG8_SA(1, 0), cA + kstep, voffA); PG8_STAGE(PG8_SB(1, 1), cB + hstepB + kstep, voffB);
;     PG8_WAIT_V(6); PG8_BAR;
.LBB0_254:
	s_waitcnt vmcnt(6)
	s_barrier
	v_lshlrev_b32_e32 v130, 6, v244
	v_lshlrev_b32_e32 v131, 2, v244
	s_lshr_b32 s76, s16, 6
	v_and_or_b32 v130, v130, s77, v80
	s_lshl_b32 s14, s21, 13
	v_and_b32_e32 v131, 32, v131
	v_bitop3_b32 v130, v130, s14, v131 bitop3:0xde
	s_lshl_b32 s14, s34, 12
	v_lshlrev_b32_e32 v132, 2, v243
	s_add_i32 s77, s76, -2
	v_lshl_or_b32 v131, v243, 6, v80
	v_and_b32_e32 v132, 32, v132
	s_cmpk_lt_u32 s17, 0x100
	v_bitop3_b32 v245, v131, s14, v132 bitop3:0xde
	s_cselect_b64 s[14:15], -1, 0
	s_or_b32 s16, s34, s21
	s_cmp_eq_u32 s16, 0
	v_readlane_b32 s20, v253, 60
	s_cselect_b64 s[16:17], -1, 0
	s_sub_i32 s82, s19, s65
	v_readlane_b32 s22, v253, 62
	v_readlane_b32 s23, v253, 63
	s_lshl_b32 s79, s19, 2
	s_lshl_b32 s81, s19, 3
	s_lshl_b32 s83, s82, 4
	s_mov_b64 s[54:55], s[22:23]
	v_readlane_b32 s21, v253, 61
	s_add_u32 s20, s54, 0x8400600
	s_addc_u32 s21, s55, 0
	s_mul_i32 s91, s19, 12
	s_bitcmp0_b32 s18, 0
	s_mov_b32 s19, 0x13400000
	s_cselect_b32 s19, s19, 0x4400000
	s_add_u32 s26, s54, s19
	s_addc_u32 s27, s55, 0
	s_add_u32 s28, s54, 0x1fa00000
	s_addc_u32 s29, s55, 0
	s_lshl_b32 s19, s18, 11
	s_and_b32 s22, s19, 0xffffe000
	s_ashr_i32 s23, s22, 31
	s_lshl_b64 s[22:23], s[22:23], 2
	s_add_u32 s19, s54, s22
	s_addc_u32 s22, s55, s23
	s_add_u32 s84, s19, 0x10000
	s_addc_u32 s85, s22, 0
	s_and_b32 s19, s18, 2
	s_cmp_eq_u32 s19, 0
	s_cselect_b64 s[30:31], -1, 0
	s_cmp_lg_u32 s19, 0
	s_cselect_b64 s[36:37], -1, 0
	s_add_u32 s50, s54, 0x13400000
	v_lshl_add_u64 v[192:193], s[28:29], 0, v[80:81]
	s_addc_u32 s51, s55, 0
	v_add_u32_e32 v80, v146, v144
	v_or_b32_e32 v131, v143, v243
	s_add_u32 s52, s54, 0x1a500000
	v_add_lshl_u32 v80, v80, v145, 1
	s_waitcnt vmcnt(4)
	v_cmp_eq_u32_e64 s[44:45], 0, v131
	v_and_b32_e32 v131, 16, v142
	v_lshlrev_b32_e32 v132, 7, v143
	s_addc_u32 s53, s55, 0
	v_lshl_add_u64 v[194:195], s[0:1], 0, v[80:81]
	v_add_u32_e32 v80, v149, v147
	v_or3_b32 v131, v131, v132, s35
	s_cmp_lt_u32 s18, 4
	v_add_lshl_u32 v80, v80, v148, 1
	s_mov_b32 s78, 0
	v_cmp_eq_u32_e64 s[42:43], 0, v143
	v_or_b32_e32 v246, 0xfffff500, v131
	v_cmp_eq_u32_e64 s[46:47], 15, v243
	s_cselect_b64 s[54:55], -1, 0
	v_or_b32_e32 v247, s35, v142
	v_lshl_add_u64 v[196:197], s[0:1], 0, v[80:81]
	v_add_u32_e32 v248, 0, v130
	s_lshl_b32 s56, s34, 2
	s_barrier
	s_branch .LBB0_257
